# phase 0 adaln_prep: the ten silu(cond) elements of a thread are loaded together instead of ten serialised load-wait round trips
# speedup vs baseline: 1.0051x; 1.0002x over previous
.LBB0_24:
	s_or_b64 exec, exec, s[2:3]
	s_movk_i32 s0, 0x1400
	v_cmp_gt_i32_e32 vcc, s0, v16
	s_and_saveexec_b64 s[0:1], vcc
	s_cbranch_execz .LBB0_31
	v_mov_b32_e32 v1, 0x20020
	ds_read_b128 v[2:5], v1
	v_lshlrev_b32_e32 v1, 2, v16
	s_waitcnt lgkmcnt(0)
	v_readfirstlane_b32 s10, v2
	v_readfirstlane_b32 s11, v3
	v_readfirstlane_b32 s12, v4
	v_readfirstlane_b32 s13, v5
	s_nop 4
	global_load_dword v2, v1, s[12:13]
	global_load_dword v3, v1, s[12:13] offset:2048
	global_load_dword v4, v1, s[10:11]
	global_load_dword v5, v1, s[10:11] offset:2048
	s_add_u32 s16, s10, 0x1000
	s_addc_u32 s17, s11, 0
	global_load_dword v6, v1, s[16:17]
	global_load_dword v7, v1, s[16:17] offset:2048
	s_add_u32 s18, s10, 0x2000
	s_addc_u32 s19, s11, 0
	global_load_dword v8, v1, s[18:19]
	global_load_dword v9, v1, s[18:19] offset:2048
	s_add_u32 s10, s10, 0x3000
	s_addc_u32 s11, s11, 0
	global_load_dword v10, v1, s[10:11]
	global_load_dword v11, v1, s[10:11] offset:2048
	v_add_u32_e32 v1, 0x10200, v1
	s_waitcnt vmcnt(9)
	v_mul_f32_e32 v12, 0xbfb8aa3b, v2
	v_exp_f32_e32 v12, v12
	s_nop 0
	v_add_f32_e32 v12, 1.0, v12
	v_rcp_f32_e32 v12, v12
	s_nop 0
	v_mul_f32_e32 v2, v2, v12
	ds_write_b32 v1, v2
	s_waitcnt vmcnt(8)
	v_mul_f32_e32 v12, 0xbfb8aa3b, v3
	v_exp_f32_e32 v12, v12
	s_nop 0
	v_add_f32_e32 v12, 1.0, v12
	v_rcp_f32_e32 v12, v12
	s_nop 0
	v_mul_f32_e32 v3, v3, v12
	ds_write_b32 v1, v3 offset:2048
	s_waitcnt vmcnt(7)
	v_mul_f32_e32 v12, 0xbfb8aa3b, v4
	v_exp_f32_e32 v12, v12
	s_nop 0
	v_add_f32_e32 v12, 1.0, v12
	v_rcp_f32_e32 v12, v12
	s_nop 0
	v_mul_f32_e32 v4, v4, v12
	ds_write_b32 v1, v4 offset:4096
	s_waitcnt vmcnt(6)
	v_mul_f32_e32 v12, 0xbfb8aa3b, v5
	v_exp_f32_e32 v12, v12
	s_nop 0
	v_add_f32_e32 v12, 1.0, v12
	v_rcp_f32_e32 v12, v12
	s_nop 0
	v_mul_f32_e32 v5, v5, v12
	ds_write_b32 v1, v5 offset:6144
	s_waitcnt vmcnt(5)
	v_mul_f32_e32 v12, 0xbfb8aa3b, v6
	v_exp_f32_e32 v12, v12
	s_nop 0
	v_add_f32_e32 v12, 1.0, v12
	v_rcp_f32_e32 v12, v12
	s_nop 0
	v_mul_f32_e32 v6, v6, v12
	ds_write_b32 v1, v6 offset:8192
	s_waitcnt vmcnt(4)
	v_mul_f32_e32 v12, 0xbfb8aa3b, v7
	v_exp_f32_e32 v12, v12
	s_nop 0
	v_add_f32_e32 v12, 1.0, v12
	v_rcp_f32_e32 v12, v12
	s_nop 0
	v_mul_f32_e32 v7, v7, v12
	ds_write_b32 v1, v7 offset:10240
	s_waitcnt vmcnt(3)
	v_mul_f32_e32 v12, 0xbfb8aa3b, v8
	v_exp_f32_e32 v12, v12
	s_nop 0
	v_add_f32_e32 v12, 1.0, v12
	v_rcp_f32_e32 v12, v12
	s_nop 0
	v_mul_f32_e32 v8, v8, v12
	ds_write_b32 v1, v8 offset:12288
	s_waitcnt vmcnt(2)
	v_mul_f32_e32 v12, 0xbfb8aa3b, v9
	v_exp_f32_e32 v12, v12
	s_nop 0
	v_add_f32_e32 v12, 1.0, v12
	v_rcp_f32_e32 v12, v12
	s_nop 0
	v_mul_f32_e32 v9, v9, v12
	ds_write_b32 v1, v9 offset:14336
	s_waitcnt vmcnt(1)
	v_mul_f32_e32 v12, 0xbfb8aa3b, v10
	v_exp_f32_e32 v12, v12
	s_nop 0
	v_add_f32_e32 v12, 1.0, v12
	v_rcp_f32_e32 v12, v12
	s_nop 0
	v_mul_f32_e32 v10, v10, v12
	ds_write_b32 v1, v10 offset:16384
	s_waitcnt vmcnt(0)
	v_mul_f32_e32 v12, 0xbfb8aa3b, v11
	v_exp_f32_e32 v12, v12
	s_nop 0
	v_add_f32_e32 v12, 1.0, v12
	v_rcp_f32_e32 v12, v12
	s_nop 0
	v_mul_f32_e32 v11, v11, v12
	ds_write_b32 v1, v11 offset:18432
